# grid barrier: non-leader WGs poll the top-level generation word directly (one hop less)
# speedup vs baseline: 1.0998x; 1.0001x over previous
.LBB0_37:
	s_or_b64 exec, exec, s[12:13]
	v_cvt_f32_u32_e32 v4, v2
	s_waitcnt vmcnt(0)
	v_readfirstlane_b32 s2, v3
	v_sub_u32_e32 v3, 0, v2
	v_rcp_iflag_f32_e32 v4, v4
	v_add_u32_e32 v5, s2, v1
	v_mul_f32_e32 v4, 0x4f7ffffe, v4
	v_cvt_u32_f32_e32 v4, v4
	v_mul_lo_u32 v1, v3, v4
	v_mul_hi_u32 v1, v4, v1
	v_add_u32_e32 v1, v4, v1
	v_mul_hi_u32 v1, v5, v1
	v_mul_lo_u32 v3, v1, v2
	v_sub_u32_e32 v3, v5, v3
	v_add_u32_e32 v4, 1, v1
	v_cmp_ge_u32_e32 vcc, v3, v2
	s_nop 1
	v_cndmask_b32_e32 v1, v1, v4, vcc
	v_sub_u32_e32 v4, v3, v2
	v_cndmask_b32_e32 v3, v3, v4, vcc
	v_add_u32_e32 v4, 1, v1
	v_cmp_ge_u32_e32 vcc, v3, v2
	v_add_u32_e32 v3, 1, v5
	s_nop 0
	v_cndmask_b32_e32 v1, v1, v4, vcc
	v_mul_lo_u32 v4, v2, v1
	v_add_u32_e32 v2, v4, v2
	v_cmp_ne_u32_e32 vcc, v3, v2
	s_and_saveexec_b64 s[2:3], vcc
	s_xor_b64 s[8:9], exec, s[2:3]
	s_cbranch_execz .LBB0_51
	s_waitcnt lgkmcnt(0)
	s_add_u32 s16, s40, 0x13fb3500
	s_addc_u32 s17, s41, 0
	v_mov_b32_e32 v0, 0
	global_load_dword v0, v0, s[16:17] sc1
	s_waitcnt vmcnt(0)
	v_cmp_eq_u32_e32 vcc, v0, v1
	s_and_saveexec_b64 s[12:13], vcc
	s_cbranch_execz .LBB0_50
	s_add_u32 s14, s40, 0x13fb0200
	s_addc_u32 s15, s41, 0
	s_mov_b32 s2, 1
	s_mov_b64 s[18:19], 0
	v_mov_b32_e32 v0, 0
	s_branch .LBB0_41

.LBB0_250:
	s_or_b64 exec, exec, s[14:15]
	v_cvt_f32_u32_e32 v4, v2
	s_waitcnt vmcnt(0)
	v_readfirstlane_b32 s2, v3
	v_sub_u32_e32 v3, 0, v2
	v_rcp_iflag_f32_e32 v4, v4
	v_add_u32_e32 v5, s2, v1
	v_mul_f32_e32 v4, 0x4f7ffffe, v4
	v_cvt_u32_f32_e32 v4, v4
	v_mul_lo_u32 v1, v3, v4
	v_mul_hi_u32 v1, v4, v1
	v_add_u32_e32 v1, v4, v1
	v_mul_hi_u32 v1, v5, v1
	v_mul_lo_u32 v3, v1, v2
	v_sub_u32_e32 v3, v5, v3
	v_add_u32_e32 v4, 1, v1
	v_cmp_ge_u32_e32 vcc, v3, v2
	s_nop 1
	v_cndmask_b32_e32 v1, v1, v4, vcc
	v_sub_u32_e32 v4, v3, v2
	v_cndmask_b32_e32 v3, v3, v4, vcc
	v_add_u32_e32 v4, 1, v1
	v_cmp_ge_u32_e32 vcc, v3, v2
	v_add_u32_e32 v3, 1, v5
	s_nop 0
	v_cndmask_b32_e32 v1, v1, v4, vcc
	v_mul_lo_u32 v4, v2, v1
	v_add_u32_e32 v2, v4, v2
	v_cmp_ne_u32_e32 vcc, v3, v2
	s_and_saveexec_b64 s[2:3], vcc
	s_xor_b64 s[12:13], exec, s[2:3]
	s_cbranch_execz .LBB0_264
	s_waitcnt lgkmcnt(0)
	s_add_u32 s18, s40, 0x13fb3500
	s_addc_u32 s19, s41, 0
	v_mov_b32_e32 v0, 0
	global_load_dword v0, v0, s[18:19] sc1
	s_waitcnt vmcnt(0)
	v_cmp_eq_u32_e32 vcc, v0, v1
	s_and_saveexec_b64 s[14:15], vcc
	s_cbranch_execz .LBB0_263
	s_add_u32 s16, s40, 0x13fb0200
	s_addc_u32 s17, s41, 0
	s_mov_b32 s2, 1
	s_mov_b64 s[20:21], 0
	v_mov_b32_e32 v0, 0
	s_branch .LBB0_254

.LBB0_886:
	s_or_b64 exec, exec, s[12:13]
	v_cvt_f32_u32_e32 v4, v2
	s_waitcnt vmcnt(0)
	v_readfirstlane_b32 s2, v3
	v_sub_u32_e32 v3, 0, v2
	v_rcp_iflag_f32_e32 v4, v4
	v_add_u32_e32 v5, s2, v1
	v_mul_f32_e32 v4, 0x4f7ffffe, v4
	v_cvt_u32_f32_e32 v4, v4
	v_mul_lo_u32 v1, v3, v4
	v_mul_hi_u32 v1, v4, v1
	v_add_u32_e32 v1, v4, v1
	v_mul_hi_u32 v1, v5, v1
	v_mul_lo_u32 v3, v1, v2
	v_sub_u32_e32 v3, v5, v3
	v_add_u32_e32 v4, 1, v1
	v_cmp_ge_u32_e32 vcc, v3, v2
	s_nop 1
	v_cndmask_b32_e32 v1, v1, v4, vcc
	v_sub_u32_e32 v4, v3, v2
	v_cndmask_b32_e32 v3, v3, v4, vcc
	v_add_u32_e32 v4, 1, v1
	v_cmp_ge_u32_e32 vcc, v3, v2
	v_add_u32_e32 v3, 1, v5
	s_nop 0
	v_cndmask_b32_e32 v1, v1, v4, vcc
	v_mul_lo_u32 v4, v2, v1
	v_add_u32_e32 v2, v4, v2
	v_cmp_ne_u32_e32 vcc, v3, v2
	s_and_saveexec_b64 s[2:3], vcc
	s_xor_b64 s[8:9], exec, s[2:3]
	s_cbranch_execz .LBB0_900
	s_waitcnt lgkmcnt(0)
	s_add_u32 s18, s40, 0x13fb3500
	s_addc_u32 s19, s41, 0
	v_mov_b32_e32 v0, 0
	global_load_dword v0, v0, s[18:19] sc1
	s_waitcnt vmcnt(0)
	v_cmp_eq_u32_e32 vcc, v0, v1
	s_and_saveexec_b64 s[12:13], vcc
	s_cbranch_execz .LBB0_899
	s_add_u32 s14, s40, 0x13fb0200
	s_addc_u32 s15, s41, 0
	s_mov_b32 s2, 1
	s_mov_b64 s[20:21], 0
	v_mov_b32_e32 v0, 0
	s_branch .LBB0_890

.LBB0_1451:
	s_or_b64 exec, exec, s[10:11]
	v_cvt_f32_u32_e32 v4, v2
	s_waitcnt vmcnt(0)
	v_readfirstlane_b32 s2, v3
	v_sub_u32_e32 v3, 0, v2
	v_rcp_iflag_f32_e32 v4, v4
	v_add_u32_e32 v5, s2, v1
	v_mul_f32_e32 v4, 0x4f7ffffe, v4
	v_cvt_u32_f32_e32 v4, v4
	v_mul_lo_u32 v1, v3, v4
	v_mul_hi_u32 v1, v4, v1
	v_add_u32_e32 v1, v4, v1
	v_mul_hi_u32 v1, v5, v1
	v_mul_lo_u32 v3, v1, v2
	v_sub_u32_e32 v3, v5, v3
	v_add_u32_e32 v4, 1, v1
	v_cmp_ge_u32_e32 vcc, v3, v2
	s_nop 1
	v_cndmask_b32_e32 v1, v1, v4, vcc
	v_sub_u32_e32 v4, v3, v2
	v_cndmask_b32_e32 v3, v3, v4, vcc
	v_add_u32_e32 v4, 1, v1
	v_cmp_ge_u32_e32 vcc, v3, v2
	v_add_u32_e32 v3, 1, v5
	s_nop 0
	v_cndmask_b32_e32 v1, v1, v4, vcc
	v_mul_lo_u32 v4, v2, v1
	v_add_u32_e32 v2, v4, v2
	v_cmp_ne_u32_e32 vcc, v3, v2
	s_and_saveexec_b64 s[2:3], vcc
	s_xor_b64 s[8:9], exec, s[2:3]
	s_cbranch_execz .LBB0_1465
	s_waitcnt lgkmcnt(0)
	s_add_u32 s14, s40, 0x13fb3500
	s_addc_u32 s15, s41, 0
	v_mov_b32_e32 v0, 0
	global_load_dword v0, v0, s[14:15] sc1
	s_waitcnt vmcnt(0)
	v_cmp_eq_u32_e32 vcc, v0, v1
	s_and_saveexec_b64 s[10:11], vcc
	s_cbranch_execz .LBB0_1464
	s_add_u32 s12, s40, 0x13fb0200
	s_addc_u32 s13, s41, 0
	s_mov_b32 s2, 1
	s_mov_b64 s[16:17], 0
	v_mov_b32_e32 v0, 0
	s_branch .LBB0_1455
